# v9 + SWA per-head gate loads issued with the head's q loads (no serialized load-wait chain in the SWA epilogue)
# speedup vs baseline: 1.0303x; 1.0017x over previous
.LBB0_1080:
	v_add_f32_e32 v0, v97, v96
	v_mov_b32_e32 v34, v0
	s_nop 1
	v_permlane32_swap_b32_e32 v0, v34
	v_add_f32_e32 v0, v0, v34
	v_div_scale_f32 v34, s[16:17], v0, v0, 1.0
	v_rcp_f32_e32 v35, v34
	s_lshl_b32 s4, s10, 6
	s_lshl_b32 s86, s4, 1
	s_add_i32 s10, s10, 1
	v_fma_f32 v36, -v34, v35, 1.0
	v_fmac_f32_e32 v35, v36, v35
	v_div_scale_f32 v36, vcc, 1.0, v0, 1.0
	v_mul_f32_e32 v37, v36, v35
	v_fma_f32 v38, -v34, v37, v36
	v_fmac_f32_e32 v37, v38, v35
	v_fma_f32 v34, -v34, v37, v36
	v_div_fmas_f32 v34, v34, v35, v37
	v_div_fixup_f32 v0, v34, v0, 1.0
	v_mul_f32_e32 v34, v18, v0
	v_mul_f32_e32 v35, v19, v0
	v_mul_f32_e32 v36, v20, v0
	v_mul_f32_e32 v37, v21, v0
	s_nop 0
	v_mul_f32_e32 v22, v22, v0
	v_mul_f32_e32 v23, v23, v0
	s_nop 0
	v_permlane32_swap_b32_e32 v34, v22
	v_permlane32_swap_b32_e32 v35, v23
	v_mul_f32_e32 v24, v24, v0
	v_mul_f32_e32 v25, v25, v0
	s_nop 0
	v_permlane32_swap_b32_e32 v36, v24
	v_permlane32_swap_b32_e32 v37, v25
	v_mul_f32_e32 v28, v28, v0
	v_mul_f32_e32 v29, v29, v0
	v_mul_f32_e32 v6, v6, v0
	v_mul_f32_e32 v7, v7, v0
	v_mul_f32_e32 v4, v4, v0
	v_mul_f32_e32 v5, v5, v0
	s_cmp_eq_u32 s10, 4
	v_mov_b32_e32 v18, v224
	v_mov_b32_e32 v19, v225
	v_mov_b32_e32 v20, v226
	v_mov_b32_e32 v21, v227
	v_lshlrev_b32_e32 v38, 16, v18
	v_and_b32_e32 v39, 0xffff0000, v18
	v_mul_f32_e32 v18, 0xbfb8aa3b, v38
	v_exp_f32_e32 v18, v18
	s_nop 0
	v_add_f32_e32 v18, 1.0, v18
	v_rcp_f32_e32 v40, v18
	v_mul_f32_e32 v18, 0xbfb8aa3b, v39
	v_exp_f32_e32 v18, v18
	s_nop 0
	v_add_f32_e32 v18, 1.0, v18
	v_rcp_f32_e32 v41, v18
	v_lshlrev_b32_e32 v18, 16, v19
	v_and_b32_e32 v19, 0xffff0000, v19
	v_pk_mul_f32 v[38:39], v[40:41], v[38:39]
	s_nop 0
	v_pk_mul_f32 v[34:35], v[38:39], v[34:35]
	v_mul_f32_e32 v38, 0xbfb8aa3b, v18
	v_mul_f32_e32 v39, 0xbfb8aa3b, v19
	v_exp_f32_e32 v38, v38
	v_exp_f32_e32 v39, v39
	v_add_f32_e32 v38, 1.0, v38
	v_add_f32_e32 v39, 1.0, v39
	v_rcp_f32_e32 v38, v38
	v_rcp_f32_e32 v39, v39
	s_nop 0
	v_pk_mul_f32 v[18:19], v[38:39], v[18:19]
	s_nop 0
	v_pk_mul_f32 v[18:19], v[18:19], v[36:37]
	v_lshlrev_b32_e32 v36, 16, v20
	v_and_b32_e32 v37, 0xffff0000, v20
	v_mul_f32_e32 v20, 0xbfb8aa3b, v36
	v_exp_f32_e32 v20, v20
	s_nop 0
	v_add_f32_e32 v20, 1.0, v20
	v_rcp_f32_e32 v38, v20
	v_mul_f32_e32 v20, 0xbfb8aa3b, v37
	v_exp_f32_e32 v20, v20
	s_nop 0
	v_add_f32_e32 v20, 1.0, v20
	v_rcp_f32_e32 v39, v20
	v_lshlrev_b32_e32 v20, 16, v21
	v_and_b32_e32 v21, 0xffff0000, v21
	v_pk_mul_f32 v[36:37], v[38:39], v[36:37]
	s_nop 0
	v_pk_mul_f32 v[22:23], v[36:37], v[22:23]
	v_mul_f32_e32 v36, 0xbfb8aa3b, v20
	v_mul_f32_e32 v37, 0xbfb8aa3b, v21
	v_exp_f32_e32 v36, v36
	v_exp_f32_e32 v37, v37
	v_cvt_pk_bf16_f32 v22, v22, v23
	v_add_f32_e32 v36, 1.0, v36
	v_add_f32_e32 v37, 1.0, v37
	v_rcp_f32_e32 v36, v36
	v_rcp_f32_e32 v37, v37
	s_nop 0
	v_pk_mul_f32 v[20:21], v[36:37], v[20:21]
	s_nop 0
	v_pk_mul_f32 v[24:25], v[20:21], v[24:25]
	v_cvt_pk_bf16_f32 v20, v34, v35
	v_cvt_pk_bf16_f32 v21, v18, v19
	v_cvt_pk_bf16_f32 v23, v24, v25
	v_lshl_add_u64 v[18:19], v[92:93], 0, s[86:87]
	global_store_dwordx4 v[18:19], v[20:23], off offset:1024
	s_nop 0
	v_mul_f32_e32 v24, v26, v0
	v_mul_f32_e32 v26, v30, v0
	v_mul_f32_e32 v30, v32, v0
	v_mul_f32_e32 v25, v27, v0
	v_mul_f32_e32 v27, v31, v0
	v_mul_f32_e32 v31, v33, v0
	v_permlane32_swap_b32_e32 v24, v26
	v_permlane32_swap_b32_e32 v25, v27
	v_permlane32_swap_b32_e32 v28, v30
	v_permlane32_swap_b32_e32 v29, v31
	v_mov_b32_e32 v20, v228
	v_mov_b32_e32 v21, v229
	v_mov_b32_e32 v22, v230
	v_mov_b32_e32 v23, v231
	v_lshlrev_b32_e32 v32, 16, v20
	v_and_b32_e32 v33, 0xffff0000, v20
	v_mul_f32_e32 v20, 0xbfb8aa3b, v32
	v_exp_f32_e32 v20, v20
	s_nop 0
	v_add_f32_e32 v20, 1.0, v20
	v_rcp_f32_e32 v34, v20
	v_mul_f32_e32 v20, 0xbfb8aa3b, v33
	v_exp_f32_e32 v20, v20
	s_nop 0
	v_add_f32_e32 v20, 1.0, v20
	v_rcp_f32_e32 v35, v20
	v_lshlrev_b32_e32 v20, 16, v21
	v_and_b32_e32 v21, 0xffff0000, v21
	v_pk_mul_f32 v[32:33], v[34:35], v[32:33]
	s_nop 0
	v_pk_mul_f32 v[24:25], v[32:33], v[24:25]
	v_mul_f32_e32 v32, 0xbfb8aa3b, v20
	v_mul_f32_e32 v33, 0xbfb8aa3b, v21
	v_exp_f32_e32 v32, v32
	v_exp_f32_e32 v33, v33
	v_add_f32_e32 v32, 1.0, v32
	v_add_f32_e32 v33, 1.0, v33
	v_rcp_f32_e32 v32, v32
	v_rcp_f32_e32 v33, v33
	s_nop 0
	v_pk_mul_f32 v[20:21], v[32:33], v[20:21]
	s_nop 0
	v_pk_mul_f32 v[28:29], v[20:21], v[28:29]
	v_lshlrev_b32_e32 v20, 16, v22
	v_and_b32_e32 v21, 0xffff0000, v22
	v_mul_f32_e32 v22, 0xbfb8aa3b, v20
	v_exp_f32_e32 v22, v22
	s_nop 0
	v_add_f32_e32 v22, 1.0, v22
	v_rcp_f32_e32 v32, v22
	v_mul_f32_e32 v22, 0xbfb8aa3b, v21
	v_exp_f32_e32 v22, v22
	s_nop 0
	v_add_f32_e32 v22, 1.0, v22
	v_rcp_f32_e32 v33, v22
	s_nop 0
	v_pk_mul_f32 v[20:21], v[32:33], v[20:21]
	s_nop 0
	v_pk_mul_f32 v[26:27], v[20:21], v[26:27]
	v_lshlrev_b32_e32 v20, 16, v23
	v_and_b32_e32 v21, 0xffff0000, v23
	v_mul_f32_e32 v22, 0xbfb8aa3b, v20
	v_mul_f32_e32 v23, 0xbfb8aa3b, v21
	v_exp_f32_e32 v22, v22
	v_exp_f32_e32 v23, v23
	v_add_f32_e32 v22, 1.0, v22
	v_add_f32_e32 v23, 1.0, v23
	v_rcp_f32_e32 v22, v22
	v_rcp_f32_e32 v23, v23
	s_nop 0
	v_pk_mul_f32 v[20:21], v[22:23], v[20:21]
	s_nop 0
	v_pk_mul_f32 v[30:31], v[20:21], v[30:31]
	v_cvt_pk_bf16_f32 v20, v24, v25
	v_cvt_pk_bf16_f32 v21, v28, v29
	v_cvt_pk_bf16_f32 v22, v26, v27
	v_cvt_pk_bf16_f32 v23, v30, v31
	global_store_dwordx4 v[18:19], v[20:23], off offset:1056
	s_nop 0
	s_nop 0
	v_mul_f32_e32 v20, v2, v0
	v_mul_f32_e32 v2, v8, v0
	v_mul_f32_e32 v21, v3, v0
	v_mul_f32_e32 v3, v9, v0
	v_permlane32_swap_b32_e32 v20, v6
	v_permlane32_swap_b32_e32 v21, v7
	v_permlane32_swap_b32_e32 v4, v2
	v_permlane32_swap_b32_e32 v5, v3
	v_mov_b32_e32 v22, v232
	v_mov_b32_e32 v23, v233
	v_mov_b32_e32 v24, v234
	v_mov_b32_e32 v25, v235
	v_lshlrev_b32_e32 v8, 16, v22
	v_and_b32_e32 v9, 0xffff0000, v22
	v_mul_f32_e32 v22, 0xbfb8aa3b, v8
	v_exp_f32_e32 v22, v22
	s_nop 0
	v_add_f32_e32 v22, 1.0, v22
	v_rcp_f32_e32 v26, v22
	v_mul_f32_e32 v22, 0xbfb8aa3b, v9
	v_exp_f32_e32 v22, v22
	s_nop 0
	v_add_f32_e32 v22, 1.0, v22
	v_rcp_f32_e32 v27, v22
	s_nop 0
	v_pk_mul_f32 v[8:9], v[26:27], v[8:9]
	s_nop 0
	v_pk_mul_f32 v[8:9], v[8:9], v[20:21]
	v_lshlrev_b32_e32 v20, 16, v23
	v_and_b32_e32 v21, 0xffff0000, v23
	v_mul_f32_e32 v22, 0xbfb8aa3b, v20
	v_mul_f32_e32 v23, 0xbfb8aa3b, v21
	v_exp_f32_e32 v22, v22
	v_exp_f32_e32 v23, v23
	v_add_f32_e32 v22, 1.0, v22
	v_add_f32_e32 v23, 1.0, v23
	v_rcp_f32_e32 v22, v22
	v_rcp_f32_e32 v23, v23
	s_nop 0
	v_pk_mul_f32 v[20:21], v[22:23], v[20:21]
	s_nop 0
	v_pk_mul_f32 v[4:5], v[20:21], v[4:5]
	v_lshlrev_b32_e32 v20, 16, v24
	v_and_b32_e32 v21, 0xffff0000, v24
	v_mul_f32_e32 v22, 0xbfb8aa3b, v20
	v_mul_f32_e32 v23, 0xbfb8aa3b, v21
	v_exp_f32_e32 v22, v22
	v_exp_f32_e32 v23, v23
	v_add_f32_e32 v22, 1.0, v22
	v_add_f32_e32 v23, 1.0, v23
	v_rcp_f32_e32 v22, v22
	v_rcp_f32_e32 v23, v23
	s_nop 0
	v_pk_mul_f32 v[20:21], v[22:23], v[20:21]
	s_nop 0
	v_pk_mul_f32 v[6:7], v[20:21], v[6:7]
	v_lshlrev_b32_e32 v20, 16, v25
	v_and_b32_e32 v21, 0xffff0000, v25
	v_mul_f32_e32 v22, 0xbfb8aa3b, v20
	v_mul_f32_e32 v23, 0xbfb8aa3b, v21
	v_exp_f32_e32 v22, v22
	v_exp_f32_e32 v23, v23
	v_add_f32_e32 v22, 1.0, v22
	v_add_f32_e32 v23, 1.0, v23
	v_rcp_f32_e32 v22, v22
	v_rcp_f32_e32 v23, v23
	s_nop 0
	v_pk_mul_f32 v[20:21], v[22:23], v[20:21]
	s_nop 0
	v_pk_mul_f32 v[20:21], v[20:21], v[2:3]
	v_cvt_pk_bf16_f32 v2, v8, v9
	v_cvt_pk_bf16_f32 v3, v4, v5
	v_cvt_pk_bf16_f32 v4, v6, v7
	v_cvt_pk_bf16_f32 v5, v20, v21
	global_store_dwordx4 v[18:19], v[2:5], off offset:1088
	s_nop 0
	v_mul_f32_e32 v20, v10, v0
	v_mul_f32_e32 v10, v12, v0
	v_mul_f32_e32 v8, v14, v0
	v_mul_f32_e32 v21, v11, v0
	v_mul_f32_e32 v9, v15, v0
	v_mul_f32_e32 v6, v16, v0
	v_mul_f32_e32 v11, v13, v0
	v_mul_f32_e32 v7, v17, v0
	v_permlane32_swap_b32_e32 v10, v6
	s_nop 0
	v_permlane32_swap_b32_e32 v11, v7
	v_permlane32_swap_b32_e32 v20, v8
	v_permlane32_swap_b32_e32 v21, v9
	v_mov_b32_e32 v2, v236
	v_mov_b32_e32 v3, v237
	v_mov_b32_e32 v4, v238
	v_mov_b32_e32 v5, v239
	v_lshlrev_b32_e32 v12, 16, v2
	v_mul_f32_e32 v0, 0xbfb8aa3b, v12
	v_exp_f32_e32 v0, v0
	v_and_b32_e32 v13, 0xffff0000, v2
	v_lshlrev_b32_e32 v2, 16, v3
	v_and_b32_e32 v3, 0xffff0000, v3
	v_add_f32_e32 v0, 1.0, v0
	v_rcp_f32_e32 v14, v0
	v_mul_f32_e32 v0, 0xbfb8aa3b, v13
	v_exp_f32_e32 v0, v0
	s_nop 0
	v_add_f32_e32 v0, 1.0, v0
	v_rcp_f32_e32 v15, v0
	v_mul_f32_e32 v0, 0xbfb8aa3b, v2
	v_exp_f32_e32 v0, v0
	v_pk_mul_f32 v[12:13], v[14:15], v[12:13]
	s_nop 0
	v_pk_mul_f32 v[12:13], v[12:13], v[20:21]
	v_add_f32_e32 v0, 1.0, v0
	v_rcp_f32_e32 v14, v0
	v_mul_f32_e32 v0, 0xbfb8aa3b, v3
	v_exp_f32_e32 v0, v0
	s_nop 0
	v_add_f32_e32 v0, 1.0, v0
	v_rcp_f32_e32 v15, v0
	s_nop 0
	v_pk_mul_f32 v[2:3], v[14:15], v[2:3]
	s_nop 0
	v_pk_mul_f32 v[10:11], v[2:3], v[10:11]
	v_lshlrev_b32_e32 v2, 16, v4
	v_mul_f32_e32 v0, 0xbfb8aa3b, v2
	v_exp_f32_e32 v0, v0
	v_and_b32_e32 v3, 0xffff0000, v4
	v_add_f32_e32 v0, 1.0, v0
	v_rcp_f32_e32 v14, v0
	v_mul_f32_e32 v0, 0xbfb8aa3b, v3
	v_exp_f32_e32 v0, v0
	s_nop 0
	v_add_f32_e32 v0, 1.0, v0
	v_rcp_f32_e32 v15, v0
	s_nop 0
	v_pk_mul_f32 v[2:3], v[14:15], v[2:3]
	s_nop 0
	v_pk_mul_f32 v[8:9], v[2:3], v[8:9]
	v_lshlrev_b32_e32 v2, 16, v5
	v_mul_f32_e32 v0, 0xbfb8aa3b, v2
	v_exp_f32_e32 v0, v0
	v_and_b32_e32 v3, 0xffff0000, v5
	v_add_f32_e32 v0, 1.0, v0
	v_rcp_f32_e32 v4, v0
	v_mul_f32_e32 v0, 0xbfb8aa3b, v3
	v_exp_f32_e32 v0, v0
	s_nop 0
	v_add_f32_e32 v0, 1.0, v0
	v_rcp_f32_e32 v5, v0
	s_nop 0
	v_pk_mul_f32 v[2:3], v[4:5], v[2:3]
	s_nop 0
	v_pk_mul_f32 v[6:7], v[2:3], v[6:7]
	v_cvt_pk_bf16_f32 v2, v12, v13
	v_cvt_pk_bf16_f32 v3, v10, v11
	v_cvt_pk_bf16_f32 v4, v8, v9
	v_cvt_pk_bf16_f32 v5, v6, v7
	global_store_dwordx4 v[18:19], v[2:5], off offset:1120
	s_cbranch_scc1 .LBB0_1056
.LBB0_1081:
	s_lshl_b32 s86, s10, 7
	v_lshl_add_u64 v[94:95], v[90:91], 0, s[86:87]
	v_mov_b32_e32 v97, 0
	s_andn2_b64 vcc, exec, s[6:7]
	v_mov_b32_e32 v96, v88
	v_mov_b32_e32 v17, 0
	v_mov_b32_e32 v16, 0
	v_mov_b32_e32 v15, 0
	v_mov_b32_e32 v14, 0
	v_mov_b32_e32 v13, 0
	v_mov_b32_e32 v12, 0
	v_mov_b32_e32 v11, 0
	v_mov_b32_e32 v10, 0
	v_mov_b32_e32 v9, 0
	v_mov_b32_e32 v8, 0
	v_mov_b32_e32 v7, 0
	v_mov_b32_e32 v6, 0
	v_mov_b32_e32 v5, 0
	v_mov_b32_e32 v4, 0
	v_mov_b32_e32 v3, 0
	v_mov_b32_e32 v2, 0
	v_mov_b32_e32 v33, 0
	v_mov_b32_e32 v32, 0
	v_mov_b32_e32 v31, 0
	v_mov_b32_e32 v30, 0
	v_mov_b32_e32 v29, 0
	v_mov_b32_e32 v28, 0
	v_mov_b32_e32 v27, 0
	v_mov_b32_e32 v26, 0
	v_mov_b32_e32 v25, 0
	v_mov_b32_e32 v24, 0
	v_mov_b32_e32 v23, 0
	v_mov_b32_e32 v22, 0
	v_mov_b32_e32 v21, 0
	v_mov_b32_e32 v20, 0
	v_mov_b32_e32 v19, 0
	v_mov_b32_e32 v18, 0
	s_cbranch_vccnz .LBB0_1080
	global_load_dwordx4 v[70:73], v[94:95], off
	global_load_dwordx4 v[74:77], v[94:95], off offset:32
	global_load_dwordx4 v[78:81], v[94:95], off offset:64
	global_load_dwordx4 v[82:85], v[94:95], off offset:96
	global_load_dwordx4 v[224:227], v[94:95], off offset:2560
	global_load_dwordx4 v[228:231], v[94:95], off offset:2592
	global_load_dwordx4 v[232:235], v[94:95], off offset:2624
	global_load_dwordx4 v[236:239], v[94:95], off offset:2656
	s_cmp_eq_u32 s10, 1
	s_cselect_b64 vcc, -1, 0
	s_cmp_eq_u32 s10, 2
	s_waitcnt vmcnt(0)
	v_cndmask_b32_e32 v0, v66, v67, vcc
	s_cselect_b64 vcc, -1, 0
	s_cmp_eq_u32 s10, 3
	v_cndmask_b32_e32 v0, v0, v68, vcc
	s_cselect_b64 vcc, -1, 0
	v_cndmask_b32_e32 v0, v0, v69, vcc
	v_mul_f32_e32 v0, 0x3fb8aa3b, v0
	v_div_scale_f32 v2, s[4:5], s82, s82, v0
	v_rcp_f32_e32 v3, v2
	v_mov_b32_e32 v14, v1
	v_mov_b32_e32 v15, v1
	v_mov_b32_e32 v7, v1
	v_fma_f32 v4, -v2, v3, 1.0
	v_fmac_f32_e32 v3, v4, v3
	v_div_scale_f32 v4, vcc, v0, s82, v0
	v_mul_f32_e32 v5, v4, v3
	v_fma_f32 v6, -v2, v5, v4
	v_fmac_f32_e32 v5, v6, v3
	v_fma_f32 v2, -v2, v5, v4
	v_div_fmas_f32 v2, v2, v3, v5
	v_div_fixup_f32 v106, v2, s82, v0
	v_mov_b32_e32 v0, v1
	v_mov_b32_e32 v2, v1
	v_mov_b32_e32 v3, v1
	v_mov_b32_e32 v4, v1
	v_mov_b32_e32 v5, v1
	v_mov_b32_e32 v6, v1
	v_mov_b32_e32 v8, v1
	v_mov_b32_e32 v9, v1
	v_mov_b32_e32 v10, v1
	v_mov_b32_e32 v11, v1
	v_mov_b32_e32 v12, v1
	v_mov_b32_e32 v13, v1
	v_mov_b64_e32 v[32:33], v[14:15]
	v_mov_b64_e32 v[30:31], v[12:13]
	v_mov_b64_e32 v[28:29], v[10:11]
	v_mov_b64_e32 v[26:27], v[8:9]
	v_mov_b64_e32 v[24:25], v[6:7]
	v_mov_b64_e32 v[22:23], v[4:5]
	v_mov_b64_e32 v[20:21], v[2:3]
	v_mov_b64_e32 v[18:19], v[0:1]
	v_mov_b64_e32 v[16:17], v[14:15]
	v_mov_b32_e32 v102, v101
	v_mov_b32_e32 v103, v100
	v_mov_b32_e32 v104, v98
	v_mov_b32_e32 v105, v87
	s_mov_b32 s15, s9
	v_mov_b64_e32 v[14:15], v[12:13]
	v_mov_b64_e32 v[12:13], v[10:11]
	v_mov_b64_e32 v[10:11], v[8:9]
	v_mov_b64_e32 v[8:9], v[6:7]
	v_mov_b64_e32 v[6:7], v[4:5]
	v_mov_b64_e32 v[4:5], v[2:3]
	v_mov_b64_e32 v[2:3], v[0:1]
	v_mov_b64_e32 v[96:97], v[88:89]
	s_branch .LBB0_1084
